# PN trims: sum of squares as two packed-FMA chains, latch copies as 64-bit moves, row strides kept in SGPRs, 3 redundant waits removed
# speedup vs baseline: 1.0170x; 1.0017x over previous
; DI void phase_norm(const Params& p, int l, const float* xin, LAS unsigned char* lds, int G, int bid) {
;     ...
;     f32x4 w0[4][4], w1[4][4];
; #pragma unroll
;     for (int j = 0; j < 4; ++j)
; #pragma unroll
;         for (int e = 0; e < 4; ++e) { const int k = 256 * j + 4 * lane + e; w0[j][e] = *(const f32x4*)(wg + (size_t)k * 8); w1[j][e] = *(const f32x4*)(wg + (size_t)k * 8 + 4); }
;     f32x4 vn[4];
;     if (gw < M) {
; #pragma unroll
;         for (int j = 0; j < 4; ++j) vn[j] = ((const f32x4*)(xin + (size_t)gw * D) + lane)[64 * j]; }
;     for (int row = gw; row < M; row += NGW) {
;         const int b = row / S;
;         f32x4 v[4]; float ss = 0.f;
; #pragma unroll
;         for (int j = 0; j < 4; ++j) v[j] = vn[j];
;         if (row + NGW < M) {
; #pragma unroll
;             for (int j = 0; j < 4; ++j) vn[j] = ((const f32x4*)(xin + (size_t)(row + NGW) * D) + lane)[64 * j]; }
.LBB0_137:
	s_or_b64 exec, exec, s[18:19]
	v_ashrrev_i32_e32 v42, 6, v2
	v_readlane_b32 s0, v250, 2
	s_lshl_b64 s[18:19], s[26:27], 15
	v_readlane_b32 s1, v250, 3
	v_add_u32_e32 v178, s0, v42
	s_mov_b32 s0, 0x8000
	v_cmp_gt_i32_e32 vcc, s0, v178
	s_waitcnt lgkmcnt(0)
	s_barrier
	s_and_saveexec_b64 s[46:47], vcc
	s_cbranch_execz .LBB0_144
	v_readlane_b32 s0, v252, 14
	s_add_u32 s0, s0, s18
	v_readlane_b32 s1, v252, 15
	v_and_b32_e32 v43, 63, v2
	s_addc_u32 s1, s1, s19
	v_lshlrev_b32_e32 v0, 7, v43
	v_lshl_add_u64 v[44:45], s[0:1], 0, v[0:1]
	v_add_co_u32_e32 v34, vcc, s89, v44
	s_movk_i32 s6, 0x4000
	s_nop 0
	v_addc_co_u32_e32 v35, vcc, 0, v45, vcc
	s_mov_b64 s[8:9], 0x2040
	v_add_co_u32_e32 v50, vcc, s6, v44
	v_lshl_add_u64 v[46:47], v[44:45], 0, s[8:9]
	s_mov_b64 s[8:9], 0x4040
	v_addc_co_u32_e32 v51, vcc, 0, v45, vcc
	s_movk_i32 s6, 0x6000
	v_lshl_add_u64 v[62:63], v[44:45], 0, s[8:9]
	s_mov_b64 s[8:9], 0x6040
	v_add_co_u32_e32 v66, vcc, s6, v44
	v_ashrrev_i32_e32 v179, 31, v178
	v_lshl_add_u64 v[78:79], v[44:45], 0, s[8:9]
	v_addc_co_u32_e32 v67, vcc, 0, v45, vcc
	v_lshlrev_b64 v[44:45], 12, v[178:179]
	global_load_dwordx4 v[2:5], v0, s[0:1] offset:48
	global_load_dwordx4 v[6:9], v0, s[0:1] offset:32
	global_load_dwordx4 v[10:13], v0, s[0:1] offset:16
	global_load_dwordx4 v[14:17], v0, s[0:1]
	global_load_dwordx4 v[18:21], v0, s[0:1] offset:112
	global_load_dwordx4 v[22:25], v0, s[0:1] offset:96
	global_load_dwordx4 v[26:29], v0, s[0:1] offset:80
	global_load_dwordx4 v[30:33], v0, s[0:1] offset:64
	v_or_b32_e32 v94, 0x2000, v0
	v_or_b32_e32 v110, 0x4000, v0
	v_or_b32_e32 v126, 0x6000, v0
	v_lshl_add_u64 v[44:45], s[4:5], 0, v[44:45]
	v_lshlrev_b32_e32 v0, 4, v43
	v_lshl_add_u64 v[82:83], v[44:45], 0, v[0:1]
	v_and_b32_e32 v44, 64, v203
	v_add_u32_e32 v44, 64, v44
	v_xor_b32_e32 v45, 1, v203
	v_cmp_lt_i32_e32 vcc, v45, v44
	v_readlane_b32 s6, v250, 4
	v_lshlrev_b64 v[172:173], 11, v[178:179]
	v_cndmask_b32_e32 v45, v203, v45, vcc
	v_lshlrev_b32_e32 v163, 2, v45
	v_xor_b32_e32 v45, 2, v203
	v_cmp_lt_i32_e32 vcc, v45, v44
	v_add_u32_e32 v42, s6, v42
	v_and_b32_e32 v220, 15, v43
	v_lshrrev_b32_e32 v221, 1, v43
	v_and_b32_e32 v221, 24, v221
	v_or_b32_e32 v221, 0x200000, v221
	v_cmp_eq_u32_e64 s[40:41], 0, v220
	v_cndmask_b32_e32 v45, v203, v45, vcc
	v_lshlrev_b32_e32 v180, 2, v45
	v_xor_b32_e32 v45, 4, v203
	v_cmp_lt_i32_e32 vcc, v45, v44
	v_lshl_or_b32 v172, v43, 3, v172
	v_ashrrev_i32_e32 v43, 31, v42
	v_cndmask_b32_e32 v45, v203, v45, vcc
	v_lshlrev_b32_e32 v181, 2, v45
	v_xor_b32_e32 v45, 8, v203
	v_cmp_lt_i32_e32 vcc, v45, v44
	v_lshlrev_b64 v[42:43], 12, v[42:43]
	v_or_b32_e32 v42, v42, v0
	v_cndmask_b32_e32 v45, v203, v45, vcc
	v_lshlrev_b32_e32 v182, 2, v45
	v_xor_b32_e32 v45, 16, v203
	v_cmp_lt_i32_e32 vcc, v45, v44
	global_load_dwordx4 v[34:37], v[34:35], off offset:64
	s_nop 0
	global_load_dwordx4 v[38:41], v[46:47], off offset:48
	v_cndmask_b32_e32 v45, v203, v45, vcc
	v_lshlrev_b32_e32 v183, 2, v45
	v_xor_b32_e32 v45, 32, v203
	v_cmp_lt_i32_e32 vcc, v45, v44
	v_lshl_add_u64 v[174:175], s[4:5], 0, v[42:43]
	v_add_u32_e32 v185, 0, v0
	v_cndmask_b32_e32 v44, v203, v45, vcc
	v_lshlrev_b32_e32 v184, 2, v44
	global_load_dwordx4 v[42:45], v[46:47], off offset:32
	s_nop 0
	global_load_dwordx4 v[46:49], v[46:47], off offset:16
	s_nop 0
	global_load_dwordx4 v[50:53], v[50:51], off offset:64
	s_nop 0
	global_load_dwordx4 v[54:57], v[62:63], off offset:48
	global_load_dwordx4 v[58:61], v[62:63], off offset:32
	s_nop 0
	global_load_dwordx4 v[62:65], v[62:63], off offset:16
	s_nop 0
	global_load_dwordx4 v[66:69], v[66:67], off offset:64
	s_nop 0
	global_load_dwordx4 v[70:73], v[78:79], off offset:48
	global_load_dwordx4 v[74:77], v[78:79], off offset:32
	s_nop 0
	global_load_dwordx4 v[78:81], v[78:79], off offset:16
	s_nop 0
	global_load_dwordx4 v[158:161], v[82:83], off
	global_load_dwordx4 v[154:157], v[82:83], off offset:1024
	global_load_dwordx4 v[150:153], v[82:83], off offset:2048
	global_load_dwordx4 v[146:149], v[82:83], off offset:3072
	s_nop 0
	global_load_dwordx4 v[82:85], v94, s[0:1] offset:48
	global_load_dwordx4 v[86:89], v94, s[0:1] offset:32
	global_load_dwordx4 v[90:93], v94, s[0:1] offset:16
	s_nop 0
	global_load_dwordx4 v[94:97], v94, s[0:1]
	s_nop 0
	global_load_dwordx4 v[98:101], v110, s[0:1] offset:48
	global_load_dwordx4 v[102:105], v110, s[0:1] offset:32
	global_load_dwordx4 v[106:109], v110, s[0:1] offset:16
	s_nop 0
	global_load_dwordx4 v[110:113], v110, s[0:1]
	s_nop 0
	global_load_dwordx4 v[114:117], v126, s[0:1] offset:48
	global_load_dwordx4 v[118:121], v126, s[0:1] offset:32
	global_load_dwordx4 v[122:125], v126, s[0:1] offset:16
	s_nop 0
	global_load_dwordx4 v[126:129], v126, s[0:1]
	s_mov_b64 s[48:49], 0
	v_lshlrev_b64 v[176:177], 5, v[178:179]
	v_readlane_b32 s98, v250, 15
	v_readlane_b32 s99, v250, 16
	v_readlane_b32 s100, v250, 17
	v_readlane_b32 s101, v250, 18
	v_readlane_b32 s8, v250, 19
	v_readlane_b32 s9, v250, 20
	s_branch .LBB0_140
.LBB0_139:
	s_or_b64 exec, exec, s[0:1]
	s_and_b64 s[0:1], exec, s[42:43]
	s_or_b64 s[48:49], s[0:1], s[48:49]
	v_mov_b32_e32 v178, v179
	v_lshl_add_u64 v[176:177], v[176:177], 0, s[98:99]
	v_lshl_add_u64 v[172:173], v[172:173], 0, s[100:101]
	v_lshl_add_u64 v[174:175], v[174:175], 0, s[8:9]
	v_mov_b64_e32 v[158:159], v[130:131]
	v_mov_b64_e32 v[160:161], v[132:133]
	v_mov_b64_e32 v[154:155], v[134:135]
	v_mov_b64_e32 v[156:157], v[136:137]
	v_mov_b64_e32 v[150:151], v[138:139]
	v_mov_b64_e32 v[152:153], v[140:141]
	v_mov_b64_e32 v[146:147], v[142:143]
	v_mov_b64_e32 v[148:149], v[144:145]
	s_andn2_b64 exec, exec, s[48:49]
	s_cbranch_execz .LBB0_144
.LBB0_140:
	v_add_u32_e32 v179, s10, v178
	s_mov_b32 s0, 0x8000
	v_cmp_gt_i32_e32 vcc, s0, v179
	s_movk_i32 s0, 0x7fff
	v_cmp_lt_i32_e64 s[42:43], s0, v179


; DI void phase_norm(const Params& p, int l, const float* xin, LAS unsigned char* lds, int G, int bid) {
;     ...
;         for (int j = 0; j < 4; ++j) ss += (v[j].x * v[j].x + v[j].y * v[j].y) + (v[j].z * v[j].z + v[j].w * v[j].w);
;         const float rstd = 1.0f / sqrtf(wave_sum(ss) * (1.f / D) + EPS);
	s_waitcnt vmcnt(12)
	s_and_saveexec_b64 s[0:1], vcc
	s_cbranch_execz .LBB0_142
	global_load_dwordx4 v[130:133], v[174:175], off
	global_load_dwordx4 v[134:137], v[174:175], off offset:1024
	global_load_dwordx4 v[138:141], v[174:175], off offset:2048
	global_load_dwordx4 v[142:145], v[174:175], off offset:3072
.LBB0_142:
	s_or_b64 exec, exec, s[0:1]
	v_ashrrev_i32_e32 v0, 31, v178
	v_lshrrev_b32_e32 v0, 19, v0
	v_add_u32_e32 v0, v178, v0
	v_ashrrev_i32_e32 v178, 13, v0
	v_pk_mul_f32 v[186:187], v[158:159], v[158:159]
	v_pk_mul_f32 v[188:189], v[160:161], v[160:161]
	v_pk_fma_f32 v[186:187], v[154:155], v[154:155], v[186:187]
	v_pk_fma_f32 v[188:189], v[156:157], v[156:157], v[188:189]
	v_pk_fma_f32 v[186:187], v[150:151], v[150:151], v[186:187]
	v_pk_fma_f32 v[188:189], v[152:153], v[152:153], v[188:189]
	v_pk_fma_f32 v[186:187], v[146:147], v[146:147], v[186:187]
	v_pk_fma_f32 v[188:189], v[148:149], v[148:149], v[188:189]
	s_mov_b32 s0, 0xf800000
	v_lshl_add_u32 v178, v178, 12, v185
	v_pk_add_f32 v[186:187], v[186:187], v[188:189]
	s_nop 0
	v_add_f32_e32 v0, v186, v187
	v_lshl_add_u64 v[194:195], s[92:93], 0, v[172:173]
	s_nop 1
	v_add_f32_dpp v0, v0, v0 quad_perm:[1,0,3,2] row_mask:0xf bank_mask:0xf
	s_nop 1
	v_add_f32_dpp v0, v0, v0 quad_perm:[2,3,0,1] row_mask:0xf bank_mask:0xf
	s_nop 1
	v_add_f32_dpp v0, v0, v0 row_half_mirror row_mask:0xf bank_mask:0xf
	s_nop 1
	v_add_f32_dpp v0, v0, v0 row_mirror row_mask:0xf bank_mask:0xf
	s_nop 3
	v_readlane_b32 s17, v0, 0
	v_readlane_b32 s23, v0, 16
	v_readlane_b32 s28, v0, 32
	v_readlane_b32 s29, v0, 48
	s_nop 1
	v_mov_b32_e32 v0, s17
	v_mov_b32_e32 v186, s28
	v_add_f32_e32 v0, s23, v0
	v_add_f32_e32 v186, s29, v186
	v_add_f32_e32 v0, v0, v186
	v_fmamk_f32 v0, v0, 0x3a800000, v204
	v_cmp_gt_f32_e32 vcc, s0, v0
	v_mul_f32_e32 v186, 0x4f800000, v0
	s_nop 0
	v_cndmask_b32_e32 v0, v0, v186, vcc
	v_sqrt_f32_e32 v186, v0
	s_nop 0
	v_add_u32_e32 v187, -1, v186
	v_fma_f32 v188, -v187, v186, v0
	v_cmp_ge_f32_e64 s[0:1], 0, v188
	v_add_u32_e32 v188, 1, v186
	s_nop 0
	v_cndmask_b32_e64 v187, v186, v187, s[0:1]
	v_fma_f32 v186, -v188, v186, v0
	v_cmp_lt_f32_e64 s[0:1], 0, v186
	s_nop 1
	v_cndmask_b32_e64 v186, v187, v188, s[0:1]
	v_mul_f32_e32 v187, 0x37800000, v186
	v_cndmask_b32_e32 v186, v186, v187, vcc
	v_cmp_class_f32_e32 vcc, v0, v205
	s_nop 1
	v_cndmask_b32_e32 v0, v186, v0, vcc
	v_div_scale_f32 v186, s[0:1], v0, v0, 1.0
	v_rcp_f32_e32 v187, v186
	s_brev_b32 s0, 32
	v_fma_f32 v188, -v186, v187, 1.0
	v_fmac_f32_e32 v187, v188, v187
	v_div_scale_f32 v188, vcc, 1.0, v0, 1.0
	v_mul_f32_e32 v189, v188, v187
	v_fma_f32 v190, -v186, v189, v188
	v_fmac_f32_e32 v189, v190, v187
	v_fma_f32 v186, -v186, v189, v188
	v_div_fmas_f32 v186, v186, v187, v189
	v_div_fixup_f32 v0, v186, v0, 1.0
	ds_read_b128 v[186:189], v178
	ds_read_b128 v[190:193], v178 offset:16384
	v_pk_mul_f32 v[158:159], v[158:159], v[0:1] op_sel_hi:[1,0]
	v_pk_mul_f32 v[160:161], v[160:161], v[0:1] op_sel_hi:[1,0]
	v_pk_mul_f32 v[154:155], v[154:155], v[0:1] op_sel_hi:[1,0]
	v_pk_mul_f32 v[156:157], v[156:157], v[0:1] op_sel_hi:[1,0]
	s_waitcnt lgkmcnt(0)
	v_pk_fma_f32 v[158:159], v[186:187], v[158:159], v[190:191]
	v_pk_fma_f32 v[160:161], v[188:189], v[160:161], v[192:193]
	v_pk_fma_f32 v[186:187], v[14:15], v[158:159], 0 op_sel_hi:[1,0,0]
	v_pk_fma_f32 v[188:189], v[16:17], v[158:159], 0 op_sel_hi:[1,0,0]
	v_pk_fma_f32 v[186:187], v[6:7], v[158:159], v[186:187] op_sel:[0,1,0]
	v_pk_fma_f32 v[190:191], v[10:11], v[158:159], 0 op_sel_hi:[1,0,0]
	v_pk_fma_f32 v[192:193], v[12:13], v[158:159], 0 op_sel_hi:[1,0,0]
	v_pk_fma_f32 v[186:187], v[30:31], v[160:161], v[186:187] op_sel_hi:[1,0,1]
	v_pk_fma_f32 v[188:189], v[8:9], v[158:159], v[188:189] op_sel:[0,1,0]
	v_pk_fma_f32 v[192:193], v[4:5], v[158:159], v[192:193] op_sel:[0,1,0]
	v_pk_fma_f32 v[190:191], v[2:3], v[158:159], v[190:191] op_sel:[0,1,0]
	v_pk_fma_f32 v[198:199], v[22:23], v[160:161], v[186:187] op_sel:[0,1,0]
	v_cvt_pk_bf16_f32 v186, v158, v159
	v_add_co_u32_e32 v158, vcc, s0, v194
	v_cvt_pk_bf16_f32 v187, v160, v161
	s_nop 0
	v_addc_co_u32_e32 v159, vcc, 0, v195, vcc
	v_pk_fma_f32 v[188:189], v[32:33], v[160:161], v[188:189] op_sel_hi:[1,0,1]
	v_pk_fma_f32 v[190:191], v[26:27], v[160:161], v[190:191] op_sel_hi:[1,0,1]
	v_pk_fma_f32 v[192:193], v[28:29], v[160:161], v[192:193] op_sel_hi:[1,0,1]
	global_store_dwordx2 v[158:159], v[186:187], off
	v_pk_fma_f32 v[196:197], v[24:25], v[160:161], v[188:189] op_sel:[0,1,0]
	v_pk_fma_f32 v[200:201], v[20:21], v[160:161], v[192:193] op_sel:[0,1,0]
	v_pk_fma_f32 v[218:219], v[18:19], v[160:161], v[190:191] op_sel:[0,1,0]
	ds_read_b128 v[186:189], v178 offset:1024
	ds_read_b128 v[190:193], v178 offset:17408
	v_pk_mul_f32 v[150:151], v[150:151], v[0:1] op_sel_hi:[1,0]
	v_pk_mul_f32 v[152:153], v[152:153], v[0:1] op_sel_hi:[1,0]
	v_pk_mul_f32 v[146:147], v[146:147], v[0:1] op_sel_hi:[1,0]
	v_pk_mul_f32 v[148:149], v[148:149], v[0:1] op_sel_hi:[1,0]
	s_waitcnt lgkmcnt(0)
	v_pk_fma_f32 v[154:155], v[186:187], v[154:155], v[190:191]
	v_pk_fma_f32 v[156:157], v[188:189], v[156:157], v[192:193]
	s_waitcnt vmcnt(9)
; #define LAS __attribute__((address_space(3)))
; DI void phase_norm(const Params& p, int l, const float* xin, LAS unsigned char* lds, int G, int bid) {
;     ...
; #pragma unroll
;         for (int j = 0; j < 4; ++j) {
;             const int k = 256 * j + 4 * lane;
;             const f32x4 aa = *(const LAS f32x4*)(pa + b * 1024 + k), sh = *(const LAS f32x4*)(pb + b * 1024 + k);
;             const f32x4 h = (v[j] * rstd) * aa + sh;
; #pragma unroll
;             for (int e = 0; e < 4; ++e) { g0 += w0[j][e] * h[e]; g1 += w1[j][e] * h[e]; }
;             o8[64 * j] = (unsigned long long)cvt_pk_bf16(h.x, h.y) | ((unsigned long long)cvt_pk_bf16(h.z, h.w) << 32);
;         }
; #pragma unroll
;         for (int e = 0; e < 4; ++e) { g0[e] = wave_sum(g0[e]); g1[e] = wave_sum(g1[e]); }
;         if (lane == 0) { *(f32x4*)(gates + (size_t)row * 8) = g0; *(f32x4*)(gates + (size_t)row * 8 + 4) = g1; }
	v_pk_fma_f32 v[160:161], v[94:95], v[154:155], v[198:199] op_sel_hi:[1,0,1]
	v_pk_fma_f32 v[186:187], v[96:97], v[154:155], v[196:197] op_sel_hi:[1,0,1]
	v_pk_fma_f32 v[188:189], v[90:91], v[154:155], v[218:219] op_sel_hi:[1,0,1]
	v_pk_fma_f32 v[190:191], v[92:93], v[154:155], v[200:201] op_sel_hi:[1,0,1]
	v_pk_fma_f32 v[186:187], v[88:89], v[154:155], v[186:187] op_sel:[0,1,0]
	v_pk_fma_f32 v[160:161], v[86:87], v[154:155], v[160:161] op_sel:[0,1,0]
	v_pk_fma_f32 v[190:191], v[84:85], v[154:155], v[190:191] op_sel:[0,1,0]
	v_pk_fma_f32 v[188:189], v[82:83], v[154:155], v[188:189] op_sel:[0,1,0]
	v_cvt_pk_bf16_f32 v154, v154, v155
	v_cvt_pk_bf16_f32 v155, v156, v157
	v_pk_fma_f32 v[160:161], v[34:35], v[156:157], v[160:161] op_sel_hi:[1,0,1]
	v_pk_fma_f32 v[186:187], v[36:37], v[156:157], v[186:187] op_sel_hi:[1,0,1]
	v_pk_fma_f32 v[188:189], v[46:47], v[156:157], v[188:189] op_sel_hi:[1,0,1]
	v_pk_fma_f32 v[190:191], v[48:49], v[156:157], v[190:191] op_sel_hi:[1,0,1]
	global_store_dwordx2 v[158:159], v[154:155], off offset:512
	v_pk_fma_f32 v[192:193], v[44:45], v[156:157], v[186:187] op_sel:[0,1,0]
	v_pk_fma_f32 v[160:161], v[42:43], v[156:157], v[160:161] op_sel:[0,1,0]
	v_pk_fma_f32 v[190:191], v[40:41], v[156:157], v[190:191] op_sel:[0,1,0]
	v_pk_fma_f32 v[194:195], v[38:39], v[156:157], v[188:189] op_sel:[0,1,0]
	ds_read_b128 v[154:157], v178 offset:2048
	ds_read_b128 v[186:189], v178 offset:18432
	s_waitcnt lgkmcnt(0)
	v_pk_fma_f32 v[150:151], v[154:155], v[150:151], v[186:187]
	v_pk_fma_f32 v[152:153], v[156:157], v[152:153], v[188:189]
	s_waitcnt vmcnt(6)
	v_pk_fma_f32 v[154:155], v[110:111], v[150:151], v[160:161] op_sel_hi:[1,0,1]
	v_pk_fma_f32 v[156:157], v[112:113], v[150:151], v[192:193] op_sel_hi:[1,0,1]
	v_pk_fma_f32 v[160:161], v[106:107], v[150:151], v[194:195] op_sel_hi:[1,0,1]
	v_pk_fma_f32 v[186:187], v[108:109], v[150:151], v[190:191] op_sel_hi:[1,0,1]
	v_pk_fma_f32 v[156:157], v[104:105], v[150:151], v[156:157] op_sel:[0,1,0]
	v_pk_fma_f32 v[154:155], v[102:103], v[150:151], v[154:155] op_sel:[0,1,0]
	v_pk_fma_f32 v[186:187], v[100:101], v[150:151], v[186:187] op_sel:[0,1,0]
	v_pk_fma_f32 v[160:161], v[98:99], v[150:151], v[160:161] op_sel:[0,1,0]
	v_cvt_pk_bf16_f32 v150, v150, v151
	v_cvt_pk_bf16_f32 v151, v152, v153
	v_pk_fma_f32 v[154:155], v[50:51], v[152:153], v[154:155] op_sel_hi:[1,0,1]
	v_pk_fma_f32 v[156:157], v[52:53], v[152:153], v[156:157] op_sel_hi:[1,0,1]
	v_pk_fma_f32 v[160:161], v[62:63], v[152:153], v[160:161] op_sel_hi:[1,0,1]
	v_pk_fma_f32 v[186:187], v[64:65], v[152:153], v[186:187] op_sel_hi:[1,0,1]
	global_store_dwordx2 v[158:159], v[150:151], off offset:1024
	v_pk_fma_f32 v[188:189], v[60:61], v[152:153], v[156:157] op_sel:[0,1,0]
	v_pk_fma_f32 v[190:191], v[58:59], v[152:153], v[154:155] op_sel:[0,1,0]
	v_pk_fma_f32 v[186:187], v[56:57], v[152:153], v[186:187] op_sel:[0,1,0]
	v_pk_fma_f32 v[160:161], v[54:55], v[152:153], v[160:161] op_sel:[0,1,0]
	ds_read_b128 v[150:153], v178 offset:3072
	ds_read_b128 v[154:157], v178 offset:19456
	s_waitcnt lgkmcnt(0)
	v_pk_fma_f32 v[146:147], v[146:147], v[150:151], v[154:155]
	s_waitcnt vmcnt(3)
	v_pk_fma_f32 v[150:151], v[126:127], v[146:147], v[190:191] op_sel_hi:[1,0,1]
	v_pk_fma_f32 v[148:149], v[148:149], v[152:153], v[156:157]
	v_pk_fma_f32 v[150:151], v[118:119], v[146:147], v[150:151] op_sel:[0,1,0]
	v_pk_fma_f32 v[152:153], v[128:129], v[146:147], v[188:189] op_sel_hi:[1,0,1]
	v_pk_fma_f32 v[154:155], v[122:123], v[146:147], v[160:161] op_sel_hi:[1,0,1]
	v_pk_fma_f32 v[156:157], v[124:125], v[146:147], v[186:187] op_sel_hi:[1,0,1]
	v_pk_fma_f32 v[150:151], v[66:67], v[148:149], v[150:151] op_sel_hi:[1,0,1]
	v_pk_fma_f32 v[152:153], v[120:121], v[146:147], v[152:153] op_sel:[0,1,0]
	v_pk_fma_f32 v[156:157], v[116:117], v[146:147], v[156:157] op_sel:[0,1,0]
	v_pk_fma_f32 v[154:155], v[114:115], v[146:147], v[154:155] op_sel:[0,1,0]
	v_pk_fma_f32 v[160:161], v[74:75], v[148:149], v[150:151] op_sel:[0,1,0]
	v_cvt_pk_bf16_f32 v146, v146, v147
	v_cvt_pk_bf16_f32 v147, v148, v149
	global_store_dwordx2 v[158:159], v[146:147], off offset:1536
	v_pk_fma_f32 v[152:153], v[68:69], v[148:149], v[152:153] op_sel_hi:[1,0,1]
	v_pk_fma_f32 v[154:155], v[78:79], v[148:149], v[154:155] op_sel_hi:[1,0,1]
	v_pk_fma_f32 v[156:157], v[80:81], v[148:149], v[156:157] op_sel_hi:[1,0,1]
	v_pk_fma_f32 v[152:153], v[76:77], v[148:149], v[152:153] op_sel:[0,1,0]
	v_pk_fma_f32 v[150:151], v[72:73], v[148:149], v[156:157] op_sel:[0,1,0]
	v_pk_fma_f32 v[154:155], v[70:71], v[148:149], v[154:155] op_sel:[0,1,0]
	s_nop 1
	v_permlane32_swap_b32 v160, v154
	v_permlane32_swap_b32 v161, v155
	v_permlane32_swap_b32 v152, v150
	v_permlane32_swap_b32 v153, v151
	v_pk_add_f32 v[160:161], v[160:161], v[154:155]
	v_pk_add_f32 v[152:153], v[152:153], v[150:151]
	s_nop 1
	v_permlane16_swap_b32 v160, v152
	v_permlane16_swap_b32 v161, v153
	v_pk_add_f32 v[160:161], v[160:161], v[152:153]
	v_add_u32_e32 v146, v176, v221
	s_nop 0
	v_add_f32_dpp v160, v160, v160 quad_perm:[1,0,3,2] row_mask:0xf bank_mask:0xf
	v_add_f32_dpp v161, v161, v161 quad_perm:[1,0,3,2] row_mask:0xf bank_mask:0xf
	s_nop 0
	v_add_f32_dpp v160, v160, v160 quad_perm:[2,3,0,1] row_mask:0xf bank_mask:0xf
	v_add_f32_dpp v161, v161, v161 quad_perm:[2,3,0,1] row_mask:0xf bank_mask:0xf
	s_nop 0
	v_add_f32_dpp v160, v160, v160 row_half_mirror row_mask:0xf bank_mask:0xf
	v_add_f32_dpp v161, v161, v161 row_half_mirror row_mask:0xf bank_mask:0xf
	s_nop 0
	v_add_f32_dpp v160, v160, v160 row_mirror row_mask:0xf bank_mask:0xf
	v_add_f32_dpp v161, v161, v161 row_mirror row_mask:0xf bank_mask:0xf
	s_and_saveexec_b64 s[0:1], s[40:41]
	global_store_dwordx2 v146, v[160:161], s[92:93]
	s_branch .LBB0_139
